# weight-conversion loops: the 16 LDS reads per item issued together with one wait (were 16 serialized LDS round trips)
# speedup vs baseline: 1.0042x; 1.0042x over previous
.LBB0_6:
	s_or_b64 exec, exec, s[6:7]
	s_waitcnt vmcnt(0) lgkmcnt(0)
	ds_write2_b32 v45, v2, v3 offset1:1
	ds_write2_b32 v45, v4, v5 offset0:2 offset1:3
	v_add_u32_e32 v2, 0x420, v45
	ds_write2_b32 v2, v10, v11 offset1:1
	v_add_u32_e32 v2, 0x428, v45
	ds_write2_b32 v2, v12, v13 offset1:1
	v_add_u32_e32 v2, 0x840, v45
	ds_write2_b32 v2, v6, v7 offset1:1
	v_add_u32_e32 v2, 0x848, v45
	ds_write2_b32 v2, v8, v9 offset1:1
	v_add_u32_e32 v2, 0xc60, v45
	ds_write2_b32 v2, v18, v19 offset1:1
	v_add_u32_e32 v2, 0xc68, v45
	ds_write2_b32 v2, v20, v21 offset1:1
	v_add_u32_e32 v2, 0x1080, v45
	ds_write2_b32 v2, v14, v15 offset1:1
	v_add_u32_e32 v2, 0x1088, v45
	ds_write2_b32 v2, v16, v17 offset1:1
	v_add_u32_e32 v2, 0x14a0, v45
	ds_write2_b32 v2, v26, v27 offset1:1
	v_add_u32_e32 v2, 0x14a8, v45
	ds_write2_b32 v2, v28, v29 offset1:1
	v_add_u32_e32 v2, 0x18c0, v45
	ds_write2_b32 v2, v22, v23 offset1:1
	v_add_u32_e32 v2, 0x18c8, v45
	ds_write2_b32 v2, v24, v25 offset1:1
	v_add_u32_e32 v2, 0x1ce0, v45
	ds_write2_b32 v2, v30, v31 offset1:1
	v_add_u32_e32 v2, 0x1ce8, v45
	ds_write2_b32 v2, v32, v33 offset1:1
	s_waitcnt lgkmcnt(0)
	ds_read2_b32 v[50:51], v44 offset1:33
	ds_read2_b32 v[52:53], v44 offset0:66 offset1:99
	ds_read2_b32 v[54:55], v44 offset0:132 offset1:165
	ds_read2_b32 v[56:57], v44 offset0:198 offset1:231
	ds_read2_b32 v[58:59], v44 offset0:8 offset1:41
	ds_read2_b32 v[60:61], v44 offset0:74 offset1:107
	ds_read2_b32 v[62:63], v44 offset0:140 offset1:173
	ds_read2_b32 v[64:65], v44 offset0:206 offset1:239
	ds_read2_b32 v[66:67], v44 offset0:16 offset1:49
	ds_read2_b32 v[68:69], v44 offset0:82 offset1:115
	ds_read2_b32 v[70:71], v44 offset0:148 offset1:181
	ds_read2_b32 v[72:73], v44 offset0:214 offset1:247
	ds_read2_b32 v[74:75], v44 offset0:24 offset1:57
	ds_read2_b32 v[76:77], v44 offset0:90 offset1:123
	ds_read2_b32 v[78:79], v44 offset0:156 offset1:189
	ds_read2_b32 v[80:81], v44 offset0:222 offset1:255
	s_waitcnt lgkmcnt(0)
	v_cvt_pk_bf16_f32 v2, v50, v51
	v_cvt_pk_bf16_f32 v3, v52, v53
	s_sub_i32 s6, 0, s5
	v_cvt_pk_bf16_f32 v4, v54, v55
	s_add_i32 s6, s6, s8
	v_cvt_pk_bf16_f32 v5, v56, v57
	v_add_u32_e32 v6, s6, v42
	s_ashr_i32 s5, s4, 31
	v_ashrrev_i32_e32 v7, 31, v6
	v_lshl_add_u64 v[8:9], s[4:5], 1, v[36:37]
	v_lshlrev_b64 v[10:11], 12, v[6:7]
	v_lshl_add_u64 v[10:11], v[8:9], 0, v[10:11]
	global_store_dwordx4 v[10:11], v[2:5], off
	s_nop 1
	s_add_i32 s1, s1, s68
	v_cvt_pk_bf16_f32 v2, v58, v59
	v_cvt_pk_bf16_f32 v3, v60, v61
	v_cvt_pk_bf16_f32 v4, v62, v63
	v_cvt_pk_bf16_f32 v5, v64, v65
	v_add_u32_e32 v10, 8, v6
	v_ashrrev_i32_e32 v11, 31, v10
	v_lshlrev_b64 v[10:11], 12, v[10:11]
	v_lshl_add_u64 v[10:11], v[8:9], 0, v[10:11]
	global_store_dwordx4 v[10:11], v[2:5], off
	s_nop 1
	s_add_i32 s8, s8, s9
	v_cvt_pk_bf16_f32 v2, v66, v67
	v_cvt_pk_bf16_f32 v3, v68, v69
	v_cvt_pk_bf16_f32 v4, v70, v71
	v_cvt_pk_bf16_f32 v5, v72, v73
	v_add_u32_e32 v10, 16, v6
	v_ashrrev_i32_e32 v11, 31, v10
	v_lshlrev_b64 v[10:11], 12, v[10:11]
	v_lshl_add_u64 v[10:11], v[8:9], 0, v[10:11]
	global_store_dwordx4 v[10:11], v[2:5], off
	s_nop 1
	v_add_u32_e32 v6, 24, v6
	v_ashrrev_i32_e32 v7, 31, v6
	v_cvt_pk_bf16_f32 v2, v74, v75
	v_lshlrev_b64 v[6:7], 12, v[6:7]
	v_cvt_pk_bf16_f32 v3, v76, v77
	v_lshl_add_u64 v[6:7], v[8:9], 0, v[6:7]
	v_cvt_pk_bf16_f32 v4, v78, v79
	v_cvt_pk_bf16_f32 v5, v80, v81
	global_store_dwordx4 v[6:7], v[2:5], off
	s_waitcnt lgkmcnt(0)
	s_cmpk_lt_i32 s1, 0x800
	s_cbranch_scc0 .LBB0_23

.LBB0_47:
	s_or_b64 exec, exec, s[8:9]
	s_waitcnt vmcnt(0) lgkmcnt(0)
	ds_write2_b32 v43, v2, v3 offset1:1
	ds_write2_b32 v43, v4, v5 offset0:2 offset1:3
	v_add_u32_e32 v2, 0x420, v43
	ds_write2_b32 v2, v10, v11 offset1:1
	v_add_u32_e32 v2, 0x428, v43
	ds_write2_b32 v2, v12, v13 offset1:1
	v_add_u32_e32 v2, 0x840, v43
	ds_write2_b32 v2, v6, v7 offset1:1
	v_add_u32_e32 v2, 0x848, v43
	ds_write2_b32 v2, v8, v9 offset1:1
	v_add_u32_e32 v2, 0xc60, v43
	ds_write2_b32 v2, v18, v19 offset1:1
	v_add_u32_e32 v2, 0xc68, v43
	ds_write2_b32 v2, v20, v21 offset1:1
	v_add_u32_e32 v2, 0x1080, v43
	ds_write2_b32 v2, v14, v15 offset1:1
	v_add_u32_e32 v2, 0x1088, v43
	ds_write2_b32 v2, v16, v17 offset1:1
	v_add_u32_e32 v2, 0x14a0, v43
	ds_write2_b32 v2, v26, v27 offset1:1
	v_add_u32_e32 v2, 0x14a8, v43
	ds_write2_b32 v2, v28, v29 offset1:1
	v_add_u32_e32 v2, 0x18c0, v43
	ds_write2_b32 v2, v22, v23 offset1:1
	v_add_u32_e32 v2, 0x18c8, v43
	ds_write2_b32 v2, v24, v25 offset1:1
	v_add_u32_e32 v2, 0x1ce0, v43
	ds_write2_b32 v2, v30, v31 offset1:1
	v_add_u32_e32 v2, 0x1ce8, v43
	ds_write2_b32 v2, v32, v33 offset1:1
	s_waitcnt lgkmcnt(0)
	ds_read2_b32 v[50:51], v42 offset1:33
	ds_read2_b32 v[52:53], v42 offset0:66 offset1:99
	ds_read2_b32 v[54:55], v42 offset0:132 offset1:165
	ds_read2_b32 v[56:57], v42 offset0:198 offset1:231
	ds_read2_b32 v[58:59], v42 offset0:8 offset1:41
	ds_read2_b32 v[60:61], v42 offset0:74 offset1:107
	ds_read2_b32 v[62:63], v42 offset0:140 offset1:173
	ds_read2_b32 v[64:65], v42 offset0:206 offset1:239
	ds_read2_b32 v[66:67], v42 offset0:16 offset1:49
	ds_read2_b32 v[68:69], v42 offset0:82 offset1:115
	ds_read2_b32 v[70:71], v42 offset0:148 offset1:181
	ds_read2_b32 v[72:73], v42 offset0:214 offset1:247
	ds_read2_b32 v[74:75], v42 offset0:24 offset1:57
	ds_read2_b32 v[76:77], v42 offset0:90 offset1:123
	ds_read2_b32 v[78:79], v42 offset0:156 offset1:189
	ds_read2_b32 v[80:81], v42 offset0:222 offset1:255
	s_waitcnt lgkmcnt(0)
	v_cvt_pk_bf16_f32 v2, v50, v51
	v_cvt_pk_bf16_f32 v3, v52, v53
	v_cvt_pk_bf16_f32 v4, v54, v55
	v_cvt_pk_bf16_f32 v5, v56, v57
	v_add_u32_e32 v6, s4, v40
	s_ashr_i32 s7, s6, 31
	v_ashrrev_i32_e32 v7, 31, v6
	v_lshl_add_u64 v[8:9], s[6:7], 1, v[36:37]
	v_lshlrev_b64 v[10:11], 12, v[6:7]
	v_lshl_add_u64 v[10:11], v[8:9], 0, v[10:11]
	global_store_dwordx4 v[10:11], v[2:5], off
	s_nop 1
	v_add_u32_e32 v12, 16, v6
	v_cvt_pk_bf16_f32 v2, v58, v59
	v_cvt_pk_bf16_f32 v3, v60, v61
	v_cvt_pk_bf16_f32 v4, v62, v63
	v_cvt_pk_bf16_f32 v5, v64, v65
	v_add_u32_e32 v10, 8, v6
	v_ashrrev_i32_e32 v11, 31, v10
	v_lshlrev_b64 v[10:11], 12, v[10:11]
	v_lshl_add_u64 v[10:11], v[8:9], 0, v[10:11]
	global_store_dwordx4 v[10:11], v[2:5], off
	s_nop 1
	v_ashrrev_i32_e32 v13, 31, v12
	v_cvt_pk_bf16_f32 v2, v66, v67
	v_cvt_pk_bf16_f32 v3, v68, v69
	v_cvt_pk_bf16_f32 v4, v70, v71
	v_cvt_pk_bf16_f32 v5, v72, v73
	v_lshlrev_b64 v[10:11], 12, v[12:13]
	v_lshl_add_u64 v[10:11], v[8:9], 0, v[10:11]
	global_store_dwordx4 v[10:11], v[2:5], off
	s_nop 1
	v_add_u32_e32 v6, 24, v6
	v_ashrrev_i32_e32 v7, 31, v6
	v_cvt_pk_bf16_f32 v2, v74, v75
	v_lshlrev_b64 v[6:7], 12, v[6:7]
	v_cvt_pk_bf16_f32 v3, v76, v77
	v_lshl_add_u64 v[6:7], v[8:9], 0, v[6:7]
	v_cvt_pk_bf16_f32 v4, v78, v79
	v_cvt_pk_bf16_f32 v5, v80, v81
	global_store_dwordx4 v[6:7], v[2:5], off
	s_waitcnt lgkmcnt(0)
	s_add_i32 s1, s1, s68
	s_add_i32 s10, s10, s11
	s_cmpk_lt_i32 s1, 0xc00
	s_cbranch_scc0 .LBB0_64

.LBB0_66:
	s_or_b64 exec, exec, s[6:7]
	s_waitcnt vmcnt(0) lgkmcnt(0)
	ds_write2_b32 v43, v2, v3 offset1:1
	ds_write2_b32 v43, v4, v5 offset0:2 offset1:3
	v_add_u32_e32 v2, 0x420, v43
	ds_write2_b32 v2, v10, v11 offset1:1
	v_add_u32_e32 v2, 0x428, v43
	ds_write2_b32 v2, v12, v13 offset1:1
	v_add_u32_e32 v2, 0x840, v43
	ds_write2_b32 v2, v6, v7 offset1:1
	v_add_u32_e32 v2, 0x848, v43
	ds_write2_b32 v2, v8, v9 offset1:1
	v_add_u32_e32 v2, 0xc60, v43
	ds_write2_b32 v2, v18, v19 offset1:1
	v_add_u32_e32 v2, 0xc68, v43
	ds_write2_b32 v2, v20, v21 offset1:1
	v_add_u32_e32 v2, 0x1080, v43
	ds_write2_b32 v2, v14, v15 offset1:1
	v_add_u32_e32 v2, 0x1088, v43
	ds_write2_b32 v2, v16, v17 offset1:1
	v_add_u32_e32 v2, 0x14a0, v43
	ds_write2_b32 v2, v26, v27 offset1:1
	v_add_u32_e32 v2, 0x14a8, v43
	ds_write2_b32 v2, v28, v29 offset1:1
	v_add_u32_e32 v2, 0x18c0, v43
	ds_write2_b32 v2, v22, v23 offset1:1
	v_add_u32_e32 v2, 0x18c8, v43
	ds_write2_b32 v2, v24, v25 offset1:1
	v_add_u32_e32 v2, 0x1ce0, v43
	ds_write2_b32 v2, v30, v31 offset1:1
	v_add_u32_e32 v2, 0x1ce8, v43
	ds_write2_b32 v2, v32, v33 offset1:1
	s_waitcnt lgkmcnt(0)
	ds_read2_b32 v[50:51], v42 offset1:33
	ds_read2_b32 v[52:53], v42 offset0:66 offset1:99
	ds_read2_b32 v[54:55], v42 offset0:132 offset1:165
	ds_read2_b32 v[56:57], v42 offset0:198 offset1:231
	ds_read2_b32 v[58:59], v42 offset0:8 offset1:41
	ds_read2_b32 v[60:61], v42 offset0:74 offset1:107
	ds_read2_b32 v[62:63], v42 offset0:140 offset1:173
	ds_read2_b32 v[64:65], v42 offset0:206 offset1:239
	ds_read2_b32 v[66:67], v42 offset0:16 offset1:49
	ds_read2_b32 v[68:69], v42 offset0:82 offset1:115
	ds_read2_b32 v[70:71], v42 offset0:148 offset1:181
	ds_read2_b32 v[72:73], v42 offset0:214 offset1:247
	ds_read2_b32 v[74:75], v42 offset0:24 offset1:57
	ds_read2_b32 v[76:77], v42 offset0:90 offset1:123
	ds_read2_b32 v[78:79], v42 offset0:156 offset1:189
	ds_read2_b32 v[80:81], v42 offset0:222 offset1:255
	s_waitcnt lgkmcnt(0)
	v_cvt_pk_bf16_f32 v2, v50, v51
	s_sub_i32 s6, 0, s5
	v_cvt_pk_bf16_f32 v3, v52, v53
	s_add_i32 s6, s6, s8
	v_cvt_pk_bf16_f32 v4, v54, v55
	v_add_u32_e32 v10, s6, v40
	v_cvt_pk_bf16_f32 v5, v56, v57
	v_add_u32_e32 v6, 0xc00, v10
	s_ashr_i32 s5, s4, 31
	v_ashrrev_i32_e32 v7, 31, v6
	v_lshl_add_u64 v[8:9], s[4:5], 1, v[36:37]
	v_lshlrev_b64 v[6:7], 12, v[6:7]
	v_lshl_add_u64 v[6:7], v[8:9], 0, v[6:7]
	global_store_dwordx4 v[6:7], v[2:5], off
	s_nop 1
	s_add_i32 s1, s1, s68
	v_cvt_pk_bf16_f32 v2, v58, v59
	v_cvt_pk_bf16_f32 v3, v60, v61
	v_cvt_pk_bf16_f32 v4, v62, v63
	v_cvt_pk_bf16_f32 v5, v64, v65
	v_add_u32_e32 v6, 0xc08, v10
	v_ashrrev_i32_e32 v7, 31, v6
	v_lshlrev_b64 v[6:7], 12, v[6:7]
	v_lshl_add_u64 v[6:7], v[8:9], 0, v[6:7]
	global_store_dwordx4 v[6:7], v[2:5], off
	s_nop 1
	s_add_i32 s8, s8, s9
	v_cvt_pk_bf16_f32 v2, v66, v67
	v_cvt_pk_bf16_f32 v3, v68, v69
	v_cvt_pk_bf16_f32 v4, v70, v71
	v_cvt_pk_bf16_f32 v5, v72, v73
	v_add_u32_e32 v6, 0xc10, v10
	v_ashrrev_i32_e32 v7, 31, v6
	v_lshlrev_b64 v[6:7], 12, v[6:7]
	v_lshl_add_u64 v[6:7], v[8:9], 0, v[6:7]
	global_store_dwordx4 v[6:7], v[2:5], off
	s_nop 1
	v_add_u32_e32 v10, 0xc18, v10
	v_ashrrev_i32_e32 v11, 31, v10
	v_cvt_pk_bf16_f32 v2, v74, v75
	v_lshlrev_b64 v[10:11], 12, v[10:11]
	v_cvt_pk_bf16_f32 v3, v76, v77
	v_lshl_add_u64 v[8:9], v[8:9], 0, v[10:11]
	v_cvt_pk_bf16_f32 v4, v78, v79
	v_cvt_pk_bf16_f32 v5, v80, v81
	global_store_dwordx4 v[8:9], v[2:5], off
	s_waitcnt lgkmcnt(0)
	s_cmpk_lt_i32 s1, 0x800
	s_cbranch_scc0 .LBB0_83

.LBB0_85:
	s_or_b64 exec, exec, s[6:7]
	s_waitcnt vmcnt(0) lgkmcnt(0)
	ds_write2_b32 v43, v2, v3 offset1:1
	ds_write2_b32 v43, v4, v5 offset0:2 offset1:3
	v_add_u32_e32 v2, 0x420, v43
	ds_write2_b32 v2, v10, v11 offset1:1
	v_add_u32_e32 v2, 0x428, v43
	ds_write2_b32 v2, v12, v13 offset1:1
	v_add_u32_e32 v2, 0x840, v43
	ds_write2_b32 v2, v6, v7 offset1:1
	v_add_u32_e32 v2, 0x848, v43
	ds_write2_b32 v2, v8, v9 offset1:1
	v_add_u32_e32 v2, 0xc60, v43
	ds_write2_b32 v2, v18, v19 offset1:1
	v_add_u32_e32 v2, 0xc68, v43
	ds_write2_b32 v2, v20, v21 offset1:1
	v_add_u32_e32 v2, 0x1080, v43
	ds_write2_b32 v2, v14, v15 offset1:1
	v_add_u32_e32 v2, 0x1088, v43
	ds_write2_b32 v2, v16, v17 offset1:1
	v_add_u32_e32 v2, 0x14a0, v43
	ds_write2_b32 v2, v26, v27 offset1:1
	v_add_u32_e32 v2, 0x14a8, v43
	ds_write2_b32 v2, v28, v29 offset1:1
	v_add_u32_e32 v2, 0x18c0, v43
	ds_write2_b32 v2, v22, v23 offset1:1
	v_add_u32_e32 v2, 0x18c8, v43
	ds_write2_b32 v2, v24, v25 offset1:1
	v_add_u32_e32 v2, 0x1ce0, v43
	ds_write2_b32 v2, v30, v31 offset1:1
	v_add_u32_e32 v2, 0x1ce8, v43
	ds_write2_b32 v2, v32, v33 offset1:1
	s_waitcnt lgkmcnt(0)
	ds_read2_b32 v[50:51], v42 offset1:33
	ds_read2_b32 v[52:53], v42 offset0:66 offset1:99
	ds_read2_b32 v[54:55], v42 offset0:132 offset1:165
	ds_read2_b32 v[56:57], v42 offset0:198 offset1:231
	ds_read2_b32 v[58:59], v42 offset0:8 offset1:41
	ds_read2_b32 v[60:61], v42 offset0:74 offset1:107
	ds_read2_b32 v[62:63], v42 offset0:140 offset1:173
	ds_read2_b32 v[64:65], v42 offset0:206 offset1:239
	ds_read2_b32 v[66:67], v42 offset0:16 offset1:49
	ds_read2_b32 v[68:69], v42 offset0:82 offset1:115
	ds_read2_b32 v[70:71], v42 offset0:148 offset1:181
	ds_read2_b32 v[72:73], v42 offset0:214 offset1:247
	ds_read2_b32 v[74:75], v42 offset0:24 offset1:57
	ds_read2_b32 v[76:77], v42 offset0:90 offset1:123
	ds_read2_b32 v[78:79], v42 offset0:156 offset1:189
	ds_read2_b32 v[80:81], v42 offset0:222 offset1:255
	s_waitcnt lgkmcnt(0)
	v_cvt_pk_bf16_f32 v2, v50, v51
	s_sub_i32 s6, 0, s4
	v_cvt_pk_bf16_f32 v3, v52, v53
	s_add_i32 s6, s6, s8
	v_cvt_pk_bf16_f32 v4, v54, v55
	v_add_u32_e32 v10, s6, v40
	v_cvt_pk_bf16_f32 v5, v56, v57
	v_add_u32_e32 v6, 0x1400, v10
	s_ashr_i32 s5, s4, 31
	v_ashrrev_i32_e32 v7, 31, v6
	v_lshl_add_u64 v[8:9], s[4:5], 1, v[36:37]
	v_lshlrev_b64 v[6:7], 12, v[6:7]
	v_lshl_add_u64 v[6:7], v[8:9], 0, v[6:7]
	global_store_dwordx4 v[6:7], v[2:5], off
	s_nop 1
	s_add_i32 s1, s1, s68
	v_cvt_pk_bf16_f32 v2, v58, v59
	v_cvt_pk_bf16_f32 v3, v60, v61
	v_cvt_pk_bf16_f32 v4, v62, v63
	v_cvt_pk_bf16_f32 v5, v64, v65
	v_add_u32_e32 v6, 0x1408, v10
	v_ashrrev_i32_e32 v7, 31, v6
	v_lshlrev_b64 v[6:7], 12, v[6:7]
	v_lshl_add_u64 v[6:7], v[8:9], 0, v[6:7]
	global_store_dwordx4 v[6:7], v[2:5], off
	s_nop 1
	s_add_i32 s8, s8, s9
	v_cvt_pk_bf16_f32 v2, v66, v67
	v_cvt_pk_bf16_f32 v3, v68, v69
	v_cvt_pk_bf16_f32 v4, v70, v71
	v_cvt_pk_bf16_f32 v5, v72, v73
	v_add_u32_e32 v6, 0x1410, v10
	v_ashrrev_i32_e32 v7, 31, v6
	v_lshlrev_b64 v[6:7], 12, v[6:7]
	v_lshl_add_u64 v[6:7], v[8:9], 0, v[6:7]
	global_store_dwordx4 v[6:7], v[2:5], off
	s_nop 1
	v_add_u32_e32 v10, 0x1418, v10
	v_ashrrev_i32_e32 v11, 31, v10
	v_cvt_pk_bf16_f32 v2, v74, v75
	v_lshlrev_b64 v[10:11], 12, v[10:11]
	v_cvt_pk_bf16_f32 v3, v76, v77
	v_lshl_add_u64 v[8:9], v[8:9], 0, v[10:11]
	v_cvt_pk_bf16_f32 v4, v78, v79
	v_cvt_pk_bf16_f32 v5, v80, v81
	global_store_dwordx4 v[8:9], v[2:5], off
	s_waitcnt lgkmcnt(0)
	s_cmp_lt_i32 s1, 64
	s_cbranch_scc0 .LBB0_102

.LBB0_130:
	s_or_b64 exec, exec, s[36:37]
	s_waitcnt vmcnt(0) lgkmcnt(0)
	ds_write2_b32 v46, v2, v3 offset1:1
	ds_write2_b32 v46, v4, v5 offset0:2 offset1:3
	v_add_u32_e32 v2, 0x420, v46
	ds_write2_b32 v2, v6, v7 offset1:1
	v_add_u32_e32 v2, 0x428, v46
	ds_write2_b32 v2, v8, v9 offset1:1
	v_add_u32_e32 v2, 0x840, v46
	ds_write2_b32 v2, v14, v15 offset1:1
	v_add_u32_e32 v2, 0x848, v46
	ds_write2_b32 v2, v16, v17 offset1:1
	v_add_u32_e32 v2, 0xc60, v46
	ds_write2_b32 v2, v10, v11 offset1:1
	v_add_u32_e32 v2, 0xc68, v46
	ds_write2_b32 v2, v12, v13 offset1:1
	v_add_u32_e32 v2, 0x1080, v46
	ds_write2_b32 v2, v22, v23 offset1:1
	v_add_u32_e32 v2, 0x1088, v46
	ds_write2_b32 v2, v24, v25 offset1:1
	v_add_u32_e32 v2, 0x14a0, v46
	ds_write2_b32 v2, v18, v19 offset1:1
	v_add_u32_e32 v2, 0x14a8, v46
	ds_write2_b32 v2, v20, v21 offset1:1
	v_add_u32_e32 v2, 0x18c0, v46
	ds_write2_b32 v2, v30, v31 offset1:1
	v_add_u32_e32 v2, 0x18c8, v46
	ds_write2_b32 v2, v32, v33 offset1:1
	v_add_u32_e32 v2, 0x1ce0, v46
	ds_write2_b32 v2, v26, v27 offset1:1
	v_add_u32_e32 v2, 0x1ce8, v46
	ds_write2_b32 v2, v28, v29 offset1:1
	s_waitcnt lgkmcnt(0)
	ds_read2_b32 v[50:51], v34 offset1:33
	ds_read2_b32 v[52:53], v34 offset0:66 offset1:99
	ds_read2_b32 v[54:55], v34 offset0:132 offset1:165
	ds_read2_b32 v[56:57], v34 offset0:198 offset1:231
	ds_read2_b32 v[58:59], v34 offset0:8 offset1:41
	ds_read2_b32 v[60:61], v34 offset0:74 offset1:107
	ds_read2_b32 v[62:63], v34 offset0:140 offset1:173
	ds_read2_b32 v[64:65], v34 offset0:206 offset1:239
	ds_read2_b32 v[66:67], v34 offset0:16 offset1:49
	ds_read2_b32 v[68:69], v34 offset0:82 offset1:115
	ds_read2_b32 v[70:71], v34 offset0:148 offset1:181
	ds_read2_b32 v[72:73], v34 offset0:214 offset1:247
	ds_read2_b32 v[74:75], v34 offset0:24 offset1:57
	ds_read2_b32 v[76:77], v34 offset0:90 offset1:123
	ds_read2_b32 v[78:79], v34 offset0:156 offset1:189
	ds_read2_b32 v[80:81], v34 offset0:222 offset1:255
	s_waitcnt lgkmcnt(0)
	v_cvt_pk_bf16_f32 v2, v50, v51
	v_cvt_pk_bf16_f32 v3, v52, v53
	s_sub_i32 s4, 0, s35
	v_cvt_pk_bf16_f32 v4, v54, v55
	s_add_i32 s4, s4, s39
	v_cvt_pk_bf16_f32 v5, v56, v57
	v_add_u32_e32 v6, s4, v44
	s_ashr_i32 s35, s34, 31
	v_ashrrev_i32_e32 v7, 31, v6
	v_lshl_add_u64 v[8:9], s[34:35], 1, v[38:39]
	v_lshlrev_b64 v[10:11], 12, v[6:7]
	v_lshl_add_u64 v[10:11], v[8:9], 0, v[10:11]
	global_store_dwordx4 v[10:11], v[2:5], off
	s_nop 1
	s_add_i32 s38, s38, s68
	v_cvt_pk_bf16_f32 v2, v58, v59
	v_cvt_pk_bf16_f32 v3, v60, v61
	v_cvt_pk_bf16_f32 v4, v62, v63
	v_cvt_pk_bf16_f32 v5, v64, v65
	v_add_u32_e32 v10, 8, v6
	v_ashrrev_i32_e32 v11, 31, v10
	v_lshlrev_b64 v[10:11], 12, v[10:11]
	v_lshl_add_u64 v[10:11], v[8:9], 0, v[10:11]
	global_store_dwordx4 v[10:11], v[2:5], off
	s_nop 1
	s_add_i32 s39, s39, s1
	v_cvt_pk_bf16_f32 v2, v66, v67
	v_cvt_pk_bf16_f32 v3, v68, v69
	v_cvt_pk_bf16_f32 v4, v70, v71
	v_cvt_pk_bf16_f32 v5, v72, v73
	v_add_u32_e32 v10, 16, v6
	v_ashrrev_i32_e32 v11, 31, v10
	v_lshlrev_b64 v[10:11], 12, v[10:11]
	v_lshl_add_u64 v[10:11], v[8:9], 0, v[10:11]
	global_store_dwordx4 v[10:11], v[2:5], off
	s_nop 1
	v_add_u32_e32 v6, 24, v6
	v_ashrrev_i32_e32 v7, 31, v6
	v_cvt_pk_bf16_f32 v2, v74, v75
	v_lshlrev_b64 v[6:7], 12, v[6:7]
	v_cvt_pk_bf16_f32 v3, v76, v77
	v_lshl_add_u64 v[6:7], v[8:9], 0, v[6:7]
	v_cvt_pk_bf16_f32 v4, v78, v79
	v_cvt_pk_bf16_f32 v5, v80, v81
	global_store_dwordx4 v[6:7], v[2:5], off
	s_waitcnt lgkmcnt(0)
	s_cmpk_lt_i32 s38, 0x1000
	s_cbranch_scc0 .LBB0_147

.LBB0_149:
	s_or_b64 exec, exec, s[30:31]
	s_waitcnt vmcnt(0) lgkmcnt(0)
	ds_write2_b32 v46, v6, v7 offset1:1
	ds_write2_b32 v46, v8, v9 offset0:2 offset1:3
	v_add_u32_e32 v6, 0x420, v46
	ds_write2_b32 v6, v2, v3 offset1:1
	v_add_u32_e32 v2, 0x428, v46
	ds_write2_b32 v2, v4, v5 offset1:1
	v_add_u32_e32 v2, 0x840, v46
	ds_write2_b32 v2, v14, v15 offset1:1
	v_add_u32_e32 v2, 0x848, v46
	ds_write2_b32 v2, v16, v17 offset1:1
	v_add_u32_e32 v2, 0xc60, v46
	ds_write2_b32 v2, v10, v11 offset1:1
	v_add_u32_e32 v2, 0xc68, v46
	ds_write2_b32 v2, v12, v13 offset1:1
	v_add_u32_e32 v2, 0x1080, v46
	ds_write2_b32 v2, v22, v23 offset1:1
	v_add_u32_e32 v2, 0x1088, v46
	ds_write2_b32 v2, v24, v25 offset1:1
	v_add_u32_e32 v2, 0x14a0, v46
	ds_write2_b32 v2, v18, v19 offset1:1
	v_add_u32_e32 v2, 0x14a8, v46
	ds_write2_b32 v2, v20, v21 offset1:1
	v_add_u32_e32 v2, 0x18c0, v46
	ds_write2_b32 v2, v30, v31 offset1:1
	v_add_u32_e32 v2, 0x18c8, v46
	ds_write2_b32 v2, v32, v33 offset1:1
	v_add_u32_e32 v2, 0x1ce0, v46
	ds_write2_b32 v2, v26, v27 offset1:1
	v_add_u32_e32 v2, 0x1ce8, v46
	ds_write2_b32 v2, v28, v29 offset1:1
	s_waitcnt lgkmcnt(0)
	ds_read2_b32 v[50:51], v34 offset1:33
	ds_read2_b32 v[52:53], v34 offset0:66 offset1:99
	ds_read2_b32 v[54:55], v34 offset0:132 offset1:165
	ds_read2_b32 v[56:57], v34 offset0:198 offset1:231
	ds_read2_b32 v[58:59], v34 offset0:8 offset1:41
	ds_read2_b32 v[60:61], v34 offset0:74 offset1:107
	ds_read2_b32 v[62:63], v34 offset0:140 offset1:173
	ds_read2_b32 v[64:65], v34 offset0:206 offset1:239
	ds_read2_b32 v[66:67], v34 offset0:16 offset1:49
	ds_read2_b32 v[68:69], v34 offset0:82 offset1:115
	ds_read2_b32 v[70:71], v34 offset0:148 offset1:181
	ds_read2_b32 v[72:73], v34 offset0:214 offset1:247
	ds_read2_b32 v[74:75], v34 offset0:24 offset1:57
	ds_read2_b32 v[76:77], v34 offset0:90 offset1:123
	ds_read2_b32 v[78:79], v34 offset0:156 offset1:189
	ds_read2_b32 v[80:81], v34 offset0:222 offset1:255
	s_waitcnt lgkmcnt(0)
	v_cvt_pk_bf16_f32 v2, v50, v51
	v_cvt_pk_bf16_f32 v3, v52, v53
	s_sub_i32 s30, 0, s5
	v_cvt_pk_bf16_f32 v4, v54, v55
	s_add_i32 s30, s30, s34
	v_cvt_pk_bf16_f32 v5, v56, v57
	v_add_u32_e32 v6, s30, v44
	s_ashr_i32 s5, s4, 31
	v_ashrrev_i32_e32 v7, 31, v6
	v_lshl_add_u64 v[8:9], s[4:5], 1, v[38:39]
	v_lshlrev_b64 v[10:11], 12, v[6:7]
	v_lshl_add_u64 v[10:11], v[8:9], 0, v[10:11]
	global_store_dwordx4 v[10:11], v[2:5], off
	s_nop 1
	s_add_i32 s36, s36, s68
	v_cvt_pk_bf16_f32 v2, v58, v59
	v_cvt_pk_bf16_f32 v3, v60, v61
	v_cvt_pk_bf16_f32 v4, v62, v63
	v_cvt_pk_bf16_f32 v5, v64, v65
	v_add_u32_e32 v10, 8, v6
	v_ashrrev_i32_e32 v11, 31, v10
	v_lshlrev_b64 v[10:11], 12, v[10:11]
	v_lshl_add_u64 v[10:11], v[8:9], 0, v[10:11]
	global_store_dwordx4 v[10:11], v[2:5], off
	s_nop 1
	s_add_i32 s34, s34, s1
	v_cvt_pk_bf16_f32 v2, v66, v67
	v_cvt_pk_bf16_f32 v3, v68, v69
	v_cvt_pk_bf16_f32 v4, v70, v71
	v_cvt_pk_bf16_f32 v5, v72, v73
	v_add_u32_e32 v10, 16, v6
	v_ashrrev_i32_e32 v11, 31, v10
	v_lshlrev_b64 v[10:11], 12, v[10:11]
	v_lshl_add_u64 v[10:11], v[8:9], 0, v[10:11]
	global_store_dwordx4 v[10:11], v[2:5], off
	s_nop 1
	v_add_u32_e32 v6, 24, v6
	v_ashrrev_i32_e32 v7, 31, v6
	v_cvt_pk_bf16_f32 v2, v74, v75
	v_lshlrev_b64 v[6:7], 12, v[6:7]
	v_cvt_pk_bf16_f32 v3, v76, v77
	v_lshl_add_u64 v[6:7], v[8:9], 0, v[6:7]
	v_cvt_pk_bf16_f32 v4, v78, v79
	v_cvt_pk_bf16_f32 v5, v80, v81
	global_store_dwordx4 v[6:7], v[2:5], off
	s_waitcnt lgkmcnt(0)
	s_cmpk_lt_i32 s36, 0x800
	s_cbranch_scc0 .LBB0_166

.LBB0_168:
	s_or_b64 exec, exec, s[36:37]
	s_waitcnt vmcnt(0) lgkmcnt(0)
	ds_write2_b32 v46, v2, v3 offset1:1
	ds_write2_b32 v46, v4, v5 offset0:2 offset1:3
	v_add_u32_e32 v2, 0x420, v46
	ds_write2_b32 v2, v6, v7 offset1:1
	v_add_u32_e32 v2, 0x428, v46
	ds_write2_b32 v2, v8, v9 offset1:1
	v_add_u32_e32 v2, 0x840, v46
	ds_write2_b32 v2, v14, v15 offset1:1
	v_add_u32_e32 v2, 0x848, v46
	ds_write2_b32 v2, v16, v17 offset1:1
	v_add_u32_e32 v2, 0xc60, v46
	ds_write2_b32 v2, v10, v11 offset1:1
	v_add_u32_e32 v2, 0xc68, v46
	ds_write2_b32 v2, v12, v13 offset1:1
	v_add_u32_e32 v2, 0x1080, v46
	ds_write2_b32 v2, v22, v23 offset1:1
	v_add_u32_e32 v2, 0x1088, v46
	ds_write2_b32 v2, v24, v25 offset1:1
	v_add_u32_e32 v2, 0x14a0, v46
	ds_write2_b32 v2, v18, v19 offset1:1
	v_add_u32_e32 v2, 0x14a8, v46
	ds_write2_b32 v2, v20, v21 offset1:1
	v_add_u32_e32 v2, 0x18c0, v46
	ds_write2_b32 v2, v30, v31 offset1:1
	v_add_u32_e32 v2, 0x18c8, v46
	ds_write2_b32 v2, v32, v33 offset1:1
	v_add_u32_e32 v2, 0x1ce0, v46
	ds_write2_b32 v2, v26, v27 offset1:1
	v_add_u32_e32 v2, 0x1ce8, v46
	ds_write2_b32 v2, v28, v29 offset1:1
	s_waitcnt lgkmcnt(0)
	ds_read2_b32 v[50:51], v34 offset1:33
	ds_read2_b32 v[52:53], v34 offset0:66 offset1:99
	ds_read2_b32 v[54:55], v34 offset0:132 offset1:165
	ds_read2_b32 v[56:57], v34 offset0:198 offset1:231
	ds_read2_b32 v[58:59], v34 offset0:8 offset1:41
	ds_read2_b32 v[60:61], v34 offset0:74 offset1:107
	ds_read2_b32 v[62:63], v34 offset0:140 offset1:173
	ds_read2_b32 v[64:65], v34 offset0:206 offset1:239
	ds_read2_b32 v[66:67], v34 offset0:16 offset1:49
	ds_read2_b32 v[68:69], v34 offset0:82 offset1:115
	ds_read2_b32 v[70:71], v34 offset0:148 offset1:181
	ds_read2_b32 v[72:73], v34 offset0:214 offset1:247
	ds_read2_b32 v[74:75], v34 offset0:24 offset1:57
	ds_read2_b32 v[76:77], v34 offset0:90 offset1:123
	ds_read2_b32 v[78:79], v34 offset0:156 offset1:189
	ds_read2_b32 v[80:81], v34 offset0:222 offset1:255
	s_waitcnt lgkmcnt(0)
	v_cvt_pk_bf16_f32 v2, v50, v51
	v_cvt_pk_bf16_f32 v3, v52, v53
	s_sub_i32 s4, 0, s35
	v_cvt_pk_bf16_f32 v4, v54, v55
	s_add_i32 s4, s4, s39
	v_cvt_pk_bf16_f32 v5, v56, v57
	v_add_u32_e32 v6, s4, v44
	s_ashr_i32 s35, s34, 31
	v_ashrrev_i32_e32 v7, 31, v6
	v_lshl_add_u64 v[8:9], s[34:35], 1, v[38:39]
	v_lshlrev_b64 v[10:11], 12, v[6:7]
	v_lshl_add_u64 v[10:11], v[8:9], 0, v[10:11]
	global_store_dwordx4 v[10:11], v[2:5], off
	s_nop 1
	s_add_i32 s38, s38, s68
	v_cvt_pk_bf16_f32 v2, v58, v59
	v_cvt_pk_bf16_f32 v3, v60, v61
	v_cvt_pk_bf16_f32 v4, v62, v63
	v_cvt_pk_bf16_f32 v5, v64, v65
	v_add_u32_e32 v10, 8, v6
	v_ashrrev_i32_e32 v11, 31, v10
	v_lshlrev_b64 v[10:11], 12, v[10:11]
	v_lshl_add_u64 v[10:11], v[8:9], 0, v[10:11]
	global_store_dwordx4 v[10:11], v[2:5], off
	s_nop 1
	s_add_i32 s39, s39, s1
	v_cvt_pk_bf16_f32 v2, v66, v67
	v_cvt_pk_bf16_f32 v3, v68, v69
	v_cvt_pk_bf16_f32 v4, v70, v71
	v_cvt_pk_bf16_f32 v5, v72, v73
	v_add_u32_e32 v10, 16, v6
	v_ashrrev_i32_e32 v11, 31, v10
	v_lshlrev_b64 v[10:11], 12, v[10:11]
	v_lshl_add_u64 v[10:11], v[8:9], 0, v[10:11]
	global_store_dwordx4 v[10:11], v[2:5], off
	s_nop 1
	v_add_u32_e32 v6, 24, v6
	v_ashrrev_i32_e32 v7, 31, v6
	v_cvt_pk_bf16_f32 v2, v74, v75
	v_lshlrev_b64 v[6:7], 12, v[6:7]
	v_cvt_pk_bf16_f32 v3, v76, v77
	v_lshl_add_u64 v[6:7], v[8:9], 0, v[6:7]
	v_cvt_pk_bf16_f32 v4, v78, v79
	v_cvt_pk_bf16_f32 v5, v80, v81
	global_store_dwordx4 v[6:7], v[2:5], off
	s_waitcnt lgkmcnt(0)
	s_cmpk_lt_i32 s38, 0x2000
	s_cbranch_scc0 .LBB0_185

.LBB0_187:
	s_or_b64 exec, exec, s[30:31]
	s_waitcnt vmcnt(0) lgkmcnt(0)
	ds_write2_b32 v46, v6, v7 offset1:1
	ds_write2_b32 v46, v8, v9 offset0:2 offset1:3
	v_add_u32_e32 v6, 0x420, v46
	ds_write2_b32 v6, v2, v3 offset1:1
	v_add_u32_e32 v2, 0x428, v46
	ds_write2_b32 v2, v4, v5 offset1:1
	v_add_u32_e32 v2, 0x840, v46
	ds_write2_b32 v2, v14, v15 offset1:1
	v_add_u32_e32 v2, 0x848, v46
	ds_write2_b32 v2, v16, v17 offset1:1
	v_add_u32_e32 v2, 0xc60, v46
	ds_write2_b32 v2, v10, v11 offset1:1
	v_add_u32_e32 v2, 0xc68, v46
	ds_write2_b32 v2, v12, v13 offset1:1
	v_add_u32_e32 v2, 0x1080, v46
	ds_write2_b32 v2, v22, v23 offset1:1
	v_add_u32_e32 v2, 0x1088, v46
	ds_write2_b32 v2, v24, v25 offset1:1
	v_add_u32_e32 v2, 0x14a0, v46
	ds_write2_b32 v2, v18, v19 offset1:1
	v_add_u32_e32 v2, 0x14a8, v46
	ds_write2_b32 v2, v20, v21 offset1:1
	v_add_u32_e32 v2, 0x18c0, v46
	ds_write2_b32 v2, v30, v31 offset1:1
	v_add_u32_e32 v2, 0x18c8, v46
	ds_write2_b32 v2, v32, v33 offset1:1
	v_add_u32_e32 v2, 0x1ce0, v46
	ds_write2_b32 v2, v26, v27 offset1:1
	v_add_u32_e32 v2, 0x1ce8, v46
	ds_write2_b32 v2, v28, v29 offset1:1
	s_waitcnt lgkmcnt(0)
	ds_read2_b32 v[50:51], v34 offset1:33
	ds_read2_b32 v[52:53], v34 offset0:66 offset1:99
	ds_read2_b32 v[54:55], v34 offset0:132 offset1:165
	ds_read2_b32 v[56:57], v34 offset0:198 offset1:231
	ds_read2_b32 v[58:59], v34 offset0:8 offset1:41
	ds_read2_b32 v[60:61], v34 offset0:74 offset1:107
	ds_read2_b32 v[62:63], v34 offset0:140 offset1:173
	ds_read2_b32 v[64:65], v34 offset0:206 offset1:239
	ds_read2_b32 v[66:67], v34 offset0:16 offset1:49
	ds_read2_b32 v[68:69], v34 offset0:82 offset1:115
	ds_read2_b32 v[70:71], v34 offset0:148 offset1:181
	ds_read2_b32 v[72:73], v34 offset0:214 offset1:247
	ds_read2_b32 v[74:75], v34 offset0:24 offset1:57
	ds_read2_b32 v[76:77], v34 offset0:90 offset1:123
	ds_read2_b32 v[78:79], v34 offset0:156 offset1:189
	ds_read2_b32 v[80:81], v34 offset0:222 offset1:255
	s_waitcnt lgkmcnt(0)
	v_cvt_pk_bf16_f32 v2, v50, v51
	v_cvt_pk_bf16_f32 v3, v52, v53
	s_sub_i32 s30, 0, s5
	v_cvt_pk_bf16_f32 v4, v54, v55
	s_add_i32 s30, s30, s12
	v_cvt_pk_bf16_f32 v5, v56, v57
	v_add_u32_e32 v6, s30, v44
	s_ashr_i32 s5, s4, 31
	v_ashrrev_i32_e32 v7, 31, v6
	v_lshl_add_u64 v[8:9], s[4:5], 1, v[38:39]
	v_lshlrev_b64 v[10:11], 14, v[6:7]
	v_lshl_add_u64 v[10:11], v[8:9], 0, v[10:11]
	global_store_dwordx4 v[10:11], v[2:5], off
	s_nop 1
	s_add_i32 s36, s36, s68
	v_cvt_pk_bf16_f32 v2, v58, v59
	v_cvt_pk_bf16_f32 v3, v60, v61
	v_cvt_pk_bf16_f32 v4, v62, v63
	v_cvt_pk_bf16_f32 v5, v64, v65
	v_add_u32_e32 v10, 8, v6
	v_ashrrev_i32_e32 v11, 31, v10
	v_lshlrev_b64 v[10:11], 14, v[10:11]
	v_lshl_add_u64 v[10:11], v[8:9], 0, v[10:11]
	global_store_dwordx4 v[10:11], v[2:5], off
	s_nop 1
	s_add_i32 s12, s12, s1
	v_cvt_pk_bf16_f32 v2, v66, v67
	v_cvt_pk_bf16_f32 v3, v68, v69
	v_cvt_pk_bf16_f32 v4, v70, v71
	v_cvt_pk_bf16_f32 v5, v72, v73
	v_add_u32_e32 v10, 16, v6
	v_ashrrev_i32_e32 v11, 31, v10
	v_lshlrev_b64 v[10:11], 14, v[10:11]
	v_lshl_add_u64 v[10:11], v[8:9], 0, v[10:11]
	global_store_dwordx4 v[10:11], v[2:5], off
	s_nop 1
	v_add_u32_e32 v6, 24, v6
	v_ashrrev_i32_e32 v7, 31, v6
	v_cvt_pk_bf16_f32 v2, v74, v75
	v_lshlrev_b64 v[6:7], 14, v[6:7]
	v_cvt_pk_bf16_f32 v3, v76, v77
	v_lshl_add_u64 v[6:7], v[8:9], 0, v[6:7]
	v_cvt_pk_bf16_f32 v4, v78, v79
	v_cvt_pk_bf16_f32 v5, v80, v81
	global_store_dwordx4 v[6:7], v[2:5], off
	s_waitcnt lgkmcnt(0)
	s_cmpk_lt_i32 s36, 0x2000
	s_cbranch_scc0 .LBB0_122

.LBB0_216:
	s_or_b64 exec, exec, s[6:7]
	s_waitcnt vmcnt(0) lgkmcnt(0)
	ds_write2_b32 v45, v2, v3 offset1:1
	ds_write2_b32 v45, v4, v5 offset0:2 offset1:3
	v_add_u32_e32 v2, 0x420, v45
	ds_write2_b32 v2, v10, v11 offset1:1
	v_add_u32_e32 v2, 0x428, v45
	ds_write2_b32 v2, v12, v13 offset1:1
	v_add_u32_e32 v2, 0x840, v45
	ds_write2_b32 v2, v6, v7 offset1:1
	v_add_u32_e32 v2, 0x848, v45
	ds_write2_b32 v2, v8, v9 offset1:1
	v_add_u32_e32 v2, 0xc60, v45
	ds_write2_b32 v2, v18, v19 offset1:1
	v_add_u32_e32 v2, 0xc68, v45
	ds_write2_b32 v2, v20, v21 offset1:1
	v_add_u32_e32 v2, 0x1080, v45
	ds_write2_b32 v2, v14, v15 offset1:1
	v_add_u32_e32 v2, 0x1088, v45
	ds_write2_b32 v2, v16, v17 offset1:1
	v_add_u32_e32 v2, 0x14a0, v45
	ds_write2_b32 v2, v26, v27 offset1:1
	v_add_u32_e32 v2, 0x14a8, v45
	ds_write2_b32 v2, v28, v29 offset1:1
	v_add_u32_e32 v2, 0x18c0, v45
	ds_write2_b32 v2, v22, v23 offset1:1
	v_add_u32_e32 v2, 0x18c8, v45
	ds_write2_b32 v2, v24, v25 offset1:1
	v_add_u32_e32 v2, 0x1ce0, v45
	ds_write2_b32 v2, v30, v31 offset1:1
	v_add_u32_e32 v2, 0x1ce8, v45
	ds_write2_b32 v2, v32, v33 offset1:1
	s_waitcnt lgkmcnt(0)
	ds_read2_b32 v[50:51], v44 offset1:33
	ds_read2_b32 v[52:53], v44 offset0:66 offset1:99
	ds_read2_b32 v[54:55], v44 offset0:132 offset1:165
	ds_read2_b32 v[56:57], v44 offset0:198 offset1:231
	ds_read2_b32 v[58:59], v44 offset0:8 offset1:41
	ds_read2_b32 v[60:61], v44 offset0:74 offset1:107
	ds_read2_b32 v[62:63], v44 offset0:140 offset1:173
	ds_read2_b32 v[64:65], v44 offset0:206 offset1:239
	ds_read2_b32 v[66:67], v44 offset0:16 offset1:49
	ds_read2_b32 v[68:69], v44 offset0:82 offset1:115
	ds_read2_b32 v[70:71], v44 offset0:148 offset1:181
	ds_read2_b32 v[72:73], v44 offset0:214 offset1:247
	ds_read2_b32 v[74:75], v44 offset0:24 offset1:57
	ds_read2_b32 v[76:77], v44 offset0:90 offset1:123
	ds_read2_b32 v[78:79], v44 offset0:156 offset1:189
	ds_read2_b32 v[80:81], v44 offset0:222 offset1:255
	s_waitcnt lgkmcnt(0)
	v_cvt_pk_bf16_f32 v2, v50, v51
	v_cvt_pk_bf16_f32 v3, v52, v53
	s_sub_i32 s6, 0, s5
	v_cvt_pk_bf16_f32 v4, v54, v55
	s_add_i32 s6, s6, s9
	v_cvt_pk_bf16_f32 v5, v56, v57
	v_add_u32_e32 v6, s6, v42
	s_ashr_i32 s5, s4, 31
	v_ashrrev_i32_e32 v7, 31, v6
	v_lshl_add_u64 v[8:9], s[4:5], 1, v[36:37]
	v_lshlrev_b64 v[10:11], 12, v[6:7]
	v_lshl_add_u64 v[10:11], v[8:9], 0, v[10:11]
	global_store_dwordx4 v[10:11], v[2:5], off
	s_nop 1
	s_add_i32 s8, s8, s68
	v_cvt_pk_bf16_f32 v2, v58, v59
	v_cvt_pk_bf16_f32 v3, v60, v61
	v_cvt_pk_bf16_f32 v4, v62, v63
	v_cvt_pk_bf16_f32 v5, v64, v65
	v_add_u32_e32 v10, 8, v6
	v_ashrrev_i32_e32 v11, 31, v10
	v_lshlrev_b64 v[10:11], 12, v[10:11]
	v_lshl_add_u64 v[10:11], v[8:9], 0, v[10:11]
	global_store_dwordx4 v[10:11], v[2:5], off
	s_nop 1
	s_add_i32 s9, s9, s1
	v_cvt_pk_bf16_f32 v2, v66, v67
	v_cvt_pk_bf16_f32 v3, v68, v69
	v_cvt_pk_bf16_f32 v4, v70, v71
	v_cvt_pk_bf16_f32 v5, v72, v73
	v_add_u32_e32 v10, 16, v6
	v_ashrrev_i32_e32 v11, 31, v10
	v_lshlrev_b64 v[10:11], 12, v[10:11]
	v_lshl_add_u64 v[10:11], v[8:9], 0, v[10:11]
	global_store_dwordx4 v[10:11], v[2:5], off
	s_nop 1
	v_add_u32_e32 v6, 24, v6
	v_ashrrev_i32_e32 v7, 31, v6
	v_cvt_pk_bf16_f32 v2, v74, v75
	v_lshlrev_b64 v[6:7], 12, v[6:7]
	v_cvt_pk_bf16_f32 v3, v76, v77
	v_lshl_add_u64 v[6:7], v[8:9], 0, v[6:7]
	v_cvt_pk_bf16_f32 v4, v78, v79
	v_cvt_pk_bf16_f32 v5, v80, v81
	global_store_dwordx4 v[6:7], v[2:5], off
	s_waitcnt lgkmcnt(0)
	s_cmpk_lt_i32 s8, 0x80
	s_cbranch_scc0 .LBB0_233

.LBB0_235:
	s_or_b64 exec, exec, s[6:7]
	s_waitcnt vmcnt(0) lgkmcnt(0)
	ds_write2_b32 v45, v2, v3 offset1:1
	ds_write2_b32 v45, v4, v5 offset0:2 offset1:3
	v_add_u32_e32 v2, 0x420, v45
	ds_write2_b32 v2, v10, v11 offset1:1
	v_add_u32_e32 v2, 0x428, v45
	ds_write2_b32 v2, v12, v13 offset1:1
	v_add_u32_e32 v2, 0x840, v45
	ds_write2_b32 v2, v6, v7 offset1:1
	v_add_u32_e32 v2, 0x848, v45
	ds_write2_b32 v2, v8, v9 offset1:1
	v_add_u32_e32 v2, 0xc60, v45
	ds_write2_b32 v2, v18, v19 offset1:1
	v_add_u32_e32 v2, 0xc68, v45
	ds_write2_b32 v2, v20, v21 offset1:1
	v_add_u32_e32 v2, 0x1080, v45
	ds_write2_b32 v2, v14, v15 offset1:1
	v_add_u32_e32 v2, 0x1088, v45
	ds_write2_b32 v2, v16, v17 offset1:1
	v_add_u32_e32 v2, 0x14a0, v45
	ds_write2_b32 v2, v26, v27 offset1:1
	v_add_u32_e32 v2, 0x14a8, v45
	ds_write2_b32 v2, v28, v29 offset1:1
	v_add_u32_e32 v2, 0x18c0, v45
	ds_write2_b32 v2, v22, v23 offset1:1
	v_add_u32_e32 v2, 0x18c8, v45
	ds_write2_b32 v2, v24, v25 offset1:1
	v_add_u32_e32 v2, 0x1ce0, v45
	ds_write2_b32 v2, v30, v31 offset1:1
	v_add_u32_e32 v2, 0x1ce8, v45
	ds_write2_b32 v2, v32, v33 offset1:1
	s_waitcnt lgkmcnt(0)
	ds_read2_b32 v[50:51], v44 offset1:33
	ds_read2_b32 v[52:53], v44 offset0:66 offset1:99
	ds_read2_b32 v[54:55], v44 offset0:132 offset1:165
	ds_read2_b32 v[56:57], v44 offset0:198 offset1:231
	ds_read2_b32 v[58:59], v44 offset0:8 offset1:41
	ds_read2_b32 v[60:61], v44 offset0:74 offset1:107
	ds_read2_b32 v[62:63], v44 offset0:140 offset1:173
	ds_read2_b32 v[64:65], v44 offset0:206 offset1:239
	ds_read2_b32 v[66:67], v44 offset0:16 offset1:49
	ds_read2_b32 v[68:69], v44 offset0:82 offset1:115
	ds_read2_b32 v[70:71], v44 offset0:148 offset1:181
	ds_read2_b32 v[72:73], v44 offset0:214 offset1:247
	ds_read2_b32 v[74:75], v44 offset0:24 offset1:57
	ds_read2_b32 v[76:77], v44 offset0:90 offset1:123
	ds_read2_b32 v[78:79], v44 offset0:156 offset1:189
	ds_read2_b32 v[80:81], v44 offset0:222 offset1:255
	s_waitcnt lgkmcnt(0)
	v_cvt_pk_bf16_f32 v2, v50, v51
	s_sub_i32 s6, 0, s5
	v_cvt_pk_bf16_f32 v3, v52, v53
	s_add_i32 s6, s6, s9
	v_cvt_pk_bf16_f32 v4, v54, v55
	v_add_u32_e32 v10, s6, v42
	v_cvt_pk_bf16_f32 v5, v56, v57
	v_add_u32_e32 v6, 0x80, v10
	s_ashr_i32 s5, s4, 31
	v_ashrrev_i32_e32 v7, 31, v6
	v_lshl_add_u64 v[8:9], s[4:5], 1, v[36:37]
	v_lshlrev_b64 v[6:7], 12, v[6:7]
	v_lshl_add_u64 v[6:7], v[8:9], 0, v[6:7]
	global_store_dwordx4 v[6:7], v[2:5], off
	s_nop 1
	s_add_i32 s8, s8, s68
	v_cvt_pk_bf16_f32 v2, v58, v59
	v_cvt_pk_bf16_f32 v3, v60, v61
	v_cvt_pk_bf16_f32 v4, v62, v63
	v_cvt_pk_bf16_f32 v5, v64, v65
	v_add_u32_e32 v6, 0x88, v10
	v_ashrrev_i32_e32 v7, 31, v6
	v_lshlrev_b64 v[6:7], 12, v[6:7]
	v_lshl_add_u64 v[6:7], v[8:9], 0, v[6:7]
	global_store_dwordx4 v[6:7], v[2:5], off
	s_nop 1
	s_add_i32 s9, s9, s1
	v_cvt_pk_bf16_f32 v2, v66, v67
	v_cvt_pk_bf16_f32 v3, v68, v69
	v_cvt_pk_bf16_f32 v4, v70, v71
	v_cvt_pk_bf16_f32 v5, v72, v73
	v_add_u32_e32 v6, 0x90, v10
	v_ashrrev_i32_e32 v7, 31, v6
	v_lshlrev_b64 v[6:7], 12, v[6:7]
	v_lshl_add_u64 v[6:7], v[8:9], 0, v[6:7]
	global_store_dwordx4 v[6:7], v[2:5], off
	s_nop 1
	v_add_u32_e32 v10, 0x98, v10
	v_ashrrev_i32_e32 v11, 31, v10
	v_cvt_pk_bf16_f32 v2, v74, v75
	v_lshlrev_b64 v[10:11], 12, v[10:11]
	v_cvt_pk_bf16_f32 v3, v76, v77
	v_lshl_add_u64 v[8:9], v[8:9], 0, v[10:11]
	v_cvt_pk_bf16_f32 v4, v78, v79
	v_cvt_pk_bf16_f32 v5, v80, v81
	global_store_dwordx4 v[8:9], v[2:5], off
	s_waitcnt lgkmcnt(0)
	s_cmpk_lt_i32 s8, 0x80
	s_cbranch_scc0 .LBB0_252

.LBB0_273:
	s_or_b64 exec, exec, s[6:7]
	s_waitcnt vmcnt(0) lgkmcnt(0)
	ds_write2_b32 v45, v2, v3 offset1:1
	ds_write2_b32 v45, v4, v5 offset0:2 offset1:3
	v_add_u32_e32 v2, 0x420, v45
	ds_write2_b32 v2, v10, v11 offset1:1
	v_add_u32_e32 v2, 0x428, v45
	ds_write2_b32 v2, v12, v13 offset1:1
	v_add_u32_e32 v2, 0x840, v45
	ds_write2_b32 v2, v6, v7 offset1:1
	v_add_u32_e32 v2, 0x848, v45
	ds_write2_b32 v2, v8, v9 offset1:1
	v_add_u32_e32 v2, 0xc60, v45
	ds_write2_b32 v2, v18, v19 offset1:1
	v_add_u32_e32 v2, 0xc68, v45
	ds_write2_b32 v2, v20, v21 offset1:1
	v_add_u32_e32 v2, 0x1080, v45
	ds_write2_b32 v2, v14, v15 offset1:1
	v_add_u32_e32 v2, 0x1088, v45
	ds_write2_b32 v2, v16, v17 offset1:1
	v_add_u32_e32 v2, 0x14a0, v45
	ds_write2_b32 v2, v26, v27 offset1:1
	v_add_u32_e32 v2, 0x14a8, v45
	ds_write2_b32 v2, v28, v29 offset1:1
	v_add_u32_e32 v2, 0x18c0, v45
	ds_write2_b32 v2, v22, v23 offset1:1
	v_add_u32_e32 v2, 0x18c8, v45
	ds_write2_b32 v2, v24, v25 offset1:1
	v_add_u32_e32 v2, 0x1ce0, v45
	ds_write2_b32 v2, v30, v31 offset1:1
	v_add_u32_e32 v2, 0x1ce8, v45
	ds_write2_b32 v2, v32, v33 offset1:1
	s_waitcnt lgkmcnt(0)
	ds_read2_b32 v[50:51], v44 offset1:33
	ds_read2_b32 v[52:53], v44 offset0:66 offset1:99
	ds_read2_b32 v[54:55], v44 offset0:132 offset1:165
	ds_read2_b32 v[56:57], v44 offset0:198 offset1:231
	ds_read2_b32 v[58:59], v44 offset0:8 offset1:41
	ds_read2_b32 v[60:61], v44 offset0:74 offset1:107
	ds_read2_b32 v[62:63], v44 offset0:140 offset1:173
	ds_read2_b32 v[64:65], v44 offset0:206 offset1:239
	ds_read2_b32 v[66:67], v44 offset0:16 offset1:49
	ds_read2_b32 v[68:69], v44 offset0:82 offset1:115
	ds_read2_b32 v[70:71], v44 offset0:148 offset1:181
	ds_read2_b32 v[72:73], v44 offset0:214 offset1:247
	ds_read2_b32 v[74:75], v44 offset0:24 offset1:57
	ds_read2_b32 v[76:77], v44 offset0:90 offset1:123
	ds_read2_b32 v[78:79], v44 offset0:156 offset1:189
	ds_read2_b32 v[80:81], v44 offset0:222 offset1:255
	s_waitcnt lgkmcnt(0)
	v_cvt_pk_bf16_f32 v2, v50, v51
	s_sub_i32 s6, 0, s5
	v_cvt_pk_bf16_f32 v3, v52, v53
	s_add_i32 s6, s6, s0
	v_cvt_pk_bf16_f32 v4, v54, v55
	v_add_u32_e32 v10, s6, v42
	v_cvt_pk_bf16_f32 v5, v56, v57
	v_add_u32_e32 v6, 0x80, v10
	s_ashr_i32 s5, s4, 31
	v_ashrrev_i32_e32 v7, 31, v6
	v_lshl_add_u64 v[8:9], s[4:5], 1, v[36:37]
	v_lshlrev_b64 v[6:7], 12, v[6:7]
	v_lshl_add_u64 v[6:7], v[8:9], 0, v[6:7]
	global_store_dwordx4 v[6:7], v[2:5], off
	s_nop 1
	s_add_i32 s8, s8, s68
	v_cvt_pk_bf16_f32 v2, v58, v59
	v_cvt_pk_bf16_f32 v3, v60, v61
	v_cvt_pk_bf16_f32 v4, v62, v63
	v_cvt_pk_bf16_f32 v5, v64, v65
	v_add_u32_e32 v6, 0x88, v10
	v_ashrrev_i32_e32 v7, 31, v6
	v_lshlrev_b64 v[6:7], 12, v[6:7]
	v_lshl_add_u64 v[6:7], v[8:9], 0, v[6:7]
	global_store_dwordx4 v[6:7], v[2:5], off
	s_nop 1
	s_add_i32 s0, s0, s1
	v_cvt_pk_bf16_f32 v2, v66, v67
	v_cvt_pk_bf16_f32 v3, v68, v69
	v_cvt_pk_bf16_f32 v4, v70, v71
	v_cvt_pk_bf16_f32 v5, v72, v73
	v_add_u32_e32 v6, 0x90, v10
	v_ashrrev_i32_e32 v7, 31, v6
	v_lshlrev_b64 v[6:7], 12, v[6:7]
	v_lshl_add_u64 v[6:7], v[8:9], 0, v[6:7]
	global_store_dwordx4 v[6:7], v[2:5], off
	s_nop 1
	v_add_u32_e32 v10, 0x98, v10
	v_ashrrev_i32_e32 v11, 31, v10
	v_cvt_pk_bf16_f32 v2, v74, v75
	v_lshlrev_b64 v[10:11], 12, v[10:11]
	v_cvt_pk_bf16_f32 v3, v76, v77
	v_lshl_add_u64 v[8:9], v[8:9], 0, v[10:11]
	v_cvt_pk_bf16_f32 v4, v78, v79
	v_cvt_pk_bf16_f32 v5, v80, v81
	global_store_dwordx4 v[8:9], v[2:5], off
	s_waitcnt lgkmcnt(0)
	s_cmpk_lt_i32 s8, 0x80
	s_cbranch_scc0 .LBB0_290
